# last phase prologue: all gate/gamma parameter-vector loads in flight at once instead of a five-step load-wait ladder
# baseline (speedup 1.0000x reference)
.LBB0_23:
	s_add_i32 s62, s92, -2
	s_ashr_i32 s64, s62, 2
	s_and_b32 s63, s62, 3
	s_cmp_lt_i32 s63, 2
	s_mov_b64 s[0:1], -1
	s_cbranch_scc1 .LBB0_58
	s_cmp_gt_i32 s63, 2
	s_cbranch_scc0 .LBB0_36
	s_cmp_gt_u32 s62, 3
	s_cbranch_scc0 .LBB0_30
	v_mov_b32_e32 v0, v186
	v_readlane_b32 s0, v255, 16
	v_ashrrev_i32_e32 v2, 6, v0
	v_add_u32_e32 v3, s48, v2
	v_ashrrev_i32_e32 v2, 31, v3
	v_xor_b32_e32 v18, s0, v2
	v_sub_u32_e32 v2, 0, v3
	v_max_i32_e32 v2, v3, v2
	v_mul_hi_u32 v4, v2, v187
	v_readlane_b32 s0, v255, 14
	s_nop 1
	v_mul_lo_u32 v5, v4, s0
	v_sub_u32_e32 v2, v2, v5
	v_add_u32_e32 v5, 1, v4
	v_cmp_le_u32_e32 vcc, s0, v2
	s_nop 1
	v_cndmask_b32_e32 v4, v4, v5, vcc
	v_subrev_u32_e32 v5, s0, v2
	v_cndmask_b32_e32 v2, v2, v5, vcc
	v_add_u32_e32 v5, 1, v4
	v_cmp_le_u32_e32 vcc, s0, v2
	s_movk_i32 s0, 0x400
	s_nop 0
	v_cndmask_b32_e32 v2, v4, v5, vcc
	v_xor_b32_e32 v19, v2, v18
	v_sub_u32_e32 v2, v19, v18
	v_mul_lo_u32 v4, v2, s31
	v_sub_u32_e32 v20, v3, v4
	v_cmp_gt_i32_e32 vcc, s0, v20
	s_and_saveexec_b64 s[18:19], vcc
	s_cbranch_execz .LBB0_29
	v_and_b32_e32 v21, 63, v0
	v_add_u32_e32 v0, 8, v2
	v_mov_b64_e32 v[2:3], s[90:91]
	v_mad_i64_i32 v[2:3], s[0:1], v0, s29, v[2:3]
	s_mov_b64 s[0:1], 0x1a02000
	s_nop 0
	v_lshl_add_u64 v[16:17], v[2:3], 0, s[0:1]
	v_mov_b64_e32 v[224:225], v[16:17]
	v_lshlrev_b32_e32 v0, 4, v21
	v_readlane_b32 s0, v253, 13
	v_lshl_add_u64 v[2:3], v[16:17], 0, v[0:1]
	v_readlane_b32 s1, v253, 14
	s_sub_u32 s34, s0, 0x1000
	s_subb_u32 s35, s1, 0
	v_mov_b32_e32 v227, 0
	v_mov_b32_e32 v226, v0
	v_add_co_u32_e32 v224, vcc, 0xfffe8000, v224
	s_nop 0
	v_addc_co_u32_e32 v225, vcc, -1, v225, vcc
	v_lshl_add_u64 v[224:225], v[224:225], 0, v[226:227]
	global_load_dwordx4 v[208:211], v[224:225], off
	global_load_dwordx4 v[212:215], v[224:225], off offset:1024
	global_load_dwordx4 v[216:219], v[224:225], off offset:2048
	global_load_dwordx4 v[220:223], v[224:225], off offset:3072
	global_load_dwordx4 v[174:177], v226, s[34:35]
	global_load_dwordx4 v[178:181], v226, s[34:35] offset:1024
	global_load_dwordx4 v[182:185], v226, s[34:35] offset:2048
	global_load_dwordx4 v[246:249], v226, s[34:35] offset:3072
	global_load_dwordx4 v[100:103], v[2:3], off offset:1024
	global_load_dwordx4 v[104:107], v[2:3], off offset:2048
	global_load_dwordx4 v[108:111], v[2:3], off offset:3072
	global_load_dwordx4 v[112:115], v0, s[0:1]
	global_load_dwordx4 v[116:119], v0, s[0:1] offset:1024
	global_load_dwordx4 v[122:125], v0, s[0:1] offset:2048
	global_load_dwordx4 v[126:129], v0, s[0:1] offset:3072
	global_load_dwordx4 v[4:7], v[2:3], off
	s_waitcnt vmcnt(0)
	v_lshlrev_b32_e32 v120, 2, v20
	v_lshl_add_u64 v[82:83], s[88:89], 0, v[0:1]
	v_lshlrev_b32_e32 v18, 12, v18
	s_mov_b64 s[34:35], 0
	global_load_dwordx4 v[8:11], v0, s[0:1]
	s_waitcnt vmcnt(0)
	v_mul_f32_e32 v3, v7, v11
	v_mul_f32_e32 v2, v6, v10
	v_or_b32_e32 v6, 0x400, v0
	v_mov_b32_e32 v7, v1
	v_mul_f32_e32 v5, v5, v9
	v_mul_f32_e32 v4, v4, v8
	v_lshl_add_u64 v[8:9], v[16:17], 0, v[6:7]
	global_load_dwordx4 v[8:11], v[8:9], off
	s_nop 0
	global_load_dwordx4 v[12:15], v6, s[0:1]
	s_waitcnt vmcnt(0)
	v_mul_f32_e32 v7, v11, v15
	v_mul_f32_e32 v6, v10, v14
	v_or_b32_e32 v10, 0x800, v0
	v_mov_b32_e32 v11, v1
	v_mul_f32_e32 v9, v9, v13
	v_mul_f32_e32 v8, v8, v12
	v_lshl_add_u64 v[12:13], v[16:17], 0, v[10:11]
	global_load_dwordx4 v[12:15], v[12:13], off
	s_nop 0
	global_load_dwordx4 v[22:25], v10, s[0:1]
	s_waitcnt vmcnt(0)
	v_mul_f32_e32 v11, v15, v25
	v_mul_f32_e32 v10, v14, v24
	v_or_b32_e32 v14, 0xc00, v0
	v_mov_b32_e32 v15, v1
	v_lshl_add_u64 v[16:17], v[16:17], 0, v[14:15]
	v_mul_f32_e32 v13, v13, v23
	v_mul_f32_e32 v12, v12, v22
	global_load_dwordx4 v[22:25], v[16:17], off
	global_load_dwordx4 v[26:29], v14, s[0:1]
	v_lshlrev_b32_e32 v0, 3, v21
	v_lshl_add_u64 v[84:85], s[12:13], 0, v[0:1]
	v_lshl_add_u32 v0, v19, 12, v120
	v_or_b32_e32 v0, 3, v0
	v_sub_u32_e32 v86, v0, v18
	s_waitcnt vmcnt(0)
	v_mul_f32_e32 v15, v25, v29
	v_mul_f32_e32 v14, v24, v28
	v_mul_f32_e32 v17, v23, v27
	v_mul_f32_e32 v16, v22, v26
	v_readlane_b32 s66, v253, 15
	v_readlane_b32 s67, v253, 16
	v_readlane_b32 s0, v255, 8
	v_readlane_b32 s1, v255, 9
	s_sub_u32 s66, s66, s88
	s_subb_u32 s67, s67, s89
	v_lshrrev_b32_e32 v244, 1, v226
	v_mov_b32_e32 v245, 0
	v_lshl_add_u64 v[206:207], s[0:1], 0, v[244:245]
	s_waitcnt vmcnt(0)
	v_mul_f32_e32 v192, v208, v174
	v_mul_f32_e32 v193, v209, v175
	v_mul_f32_e32 v190, v210, v176
	v_mul_f32_e32 v191, v211, v177
	v_mul_f32_e32 v196, v212, v178
	v_mul_f32_e32 v197, v213, v179
	v_mul_f32_e32 v194, v214, v180
	v_mul_f32_e32 v195, v215, v181
	v_mul_f32_e32 v200, v216, v182
	v_mul_f32_e32 v201, v217, v183
	v_mul_f32_e32 v198, v218, v184
	v_mul_f32_e32 v199, v219, v185
	v_mul_f32_e32 v204, v220, v246
	v_mul_f32_e32 v205, v221, v247
	v_mul_f32_e32 v202, v222, v248
	v_mul_f32_e32 v203, v223, v249
